# v76: + FoX per-wave leading-tile skip (same rigorous bound evaluated per wave inside the loop)
# speedup vs baseline: 1.0163x; 1.0163x over previous
; #define LAS __attribute__((address_space(3)))
; __device__ __forceinline__ void attn_phase(const Params& P, LAS unsigned char* lds) {
;     int tid_ = threadIdx.x; asm volatile("" : "+v"(tid_)); const int tid = tid_;
;     unsigned* ctr = (unsigned*)(P.ws + WS_CTL);
;     LAS int* misc = (LAS int*)(lds + AL_MISC);
;     const int xq = (int)(__builtin_amdgcn_s_getreg((3 << 11) | 20) & 7u);
;     const bool bounded = ((const float*)(P.ws + WS_TAB))[TAB_DBOUND] <= 60.0f;
.LBB0_418:
	v_writelane_b32 v255, s88, 3
	s_nop 1
	v_writelane_b32 v255, s89, 4
	v_writelane_b32 v255, s94, 5
	s_nop 1
	v_writelane_b32 v255, s95, 6
	s_or_b64 exec, exec, s[4:5]
	s_waitcnt lgkmcnt(0)
	v_mov_b32_e32 v0, v178
	v_mov_b32_e32 v1, 0x2000
	s_barrier
	s_getreg_b32 s3, hwreg(HW_REG_XCC_ID, 0, 4)
	global_load_dword v2, v1, s[52:53] offset:136
	global_load_dword v3, v1, s[52:53] offset:132
	s_lshr_b32 s72, s75, 16
	s_and_b32 s0, s75, 0xffff
	s_add_u32 s78, s52, 0x18324000
	s_addc_u32 s79, s53, 0
	s_add_u32 s80, s52, 0x1c324000
	s_addc_u32 s81, s53, 0
	s_add_u32 s82, s52, 0x124000
	s_addc_u32 s83, s53, 0
	s_add_u32 s60, s52, 0x2084
	s_addc_u32 s61, s53, 0
	s_add_u32 s84, s52, 0x20324000
	s_addc_u32 s85, s53, 0
	s_add_u32 s86, s52, 0x24324000
	s_addc_u32 s87, s53, 0
	s_add_u32 s88, s52, 0x28324000
	s_addc_u32 s89, s53, 0
	s_add_u32 s90, s52, 0x2c324000
	s_addc_u32 s91, s53, 0
	s_add_u32 s92, s52, 0x30324000
	s_addc_u32 s93, s53, 0
	s_mov_b32 s6, 0x22000
	s_add_u32 s62, s52, 0x2080
	s_mov_b32 s1, 0x42700000
	s_addc_u32 s63, s53, 0
	s_add_i32 s95, s6, 0x100
	s_mov_b32 s13, 0
	v_mov_b32_e32 v1, 0
	s_mov_b64 s[28:29], 0x2000
	s_movk_i32 s73, 0x4000
	s_movk_i32 s75, 0x81
	s_mov_b32 s76, 0x22100
	s_mov_b64 s[30:31], 0x4000
	s_mov_b64 s[36:37], 0x6000
	s_mov_b64 s[42:43], 0x28330000
	s_mov_b64 s[44:45], 0x28332000
	s_mov_b64 s[48:49], 0x2c330000
	s_mov_b64 s[50:51], 0x2c332000
	v_mov_b32_e32 v230, 0x358637bd
	v_mbcnt_hi_u32_b32 v179, -1, v173
	v_mov_b32_e32 v231, 0xff800000
	v_mov_b32_e32 v232, 0x100
	v_mad_u32_u24 v233, v172, s0, v254
	v_cmp_eq_u32_e64 s[4:5], 0, v0
	s_lshl_b32 s94, s0, 8
	v_mov_b32_e32 v234, s95
	v_mov_b32_e32 v235, 0x80
	s_waitcnt vmcnt(0)
	v_cmp_ge_f32_e64 s[6:7], s1, v2
	v_mov_b32_e32 v4, 0x42f00000
	v_cmp_ge_f32_e64 s[100:101], v4, v3
	v_readfirstlane_b32 s0, v3
	s_nop 3
	v_writelane_b32 v255, s0, 8
	s_branch .LBB0_421

; #define ATT_WAITV(n) asm volatile("s_waitcnt vmcnt(" #n ")" ::: "memory")
; template <int MODE>
; __device__ __forceinline__ void attn_unit(const Params& P, LAS unsigned char* lds, const int b, const int h, const int qb) {
;     ...
;     const int krow = 4 * w + (lane >> 4), kchunk = (lane & 15) ^ (krow & 15);
;     const bf16_t* kg = Kb_ + (size_t)krow * RS + kchunk * 8;
;     const int vst = 2 * w + (lane >> 5), vkey = (vst >> 2) * 8 + ((lane >> 2) & 7);
;     const bf16_t* vg = Vb_ + (size_t)vkey * RS + (vst & 3) * 32 + (lane & 3) * 8;
;     const float* cg_ = Cl + lane;
;     ...
;     const int pr = (r & 19) | ((r & 4) << 1) | ((r & 8) >> 1);
;     const unsigned kra = pr * 256, kswz = pr & 15;
;     const unsigned vra = 16384 + hh * 2048 + ((lane & 15) >> 2) * 64 + ((lane >> 4) & 1) * 32 + (lane & 3) * 8;
;     f32x16 O[4];
; #pragma unroll
;     for (int d = 0; d < 4; ++d)
; #pragma unroll
;         for (int i = 0; i < 16; ++i) O[d][i] = 0.f;
;     float m1 = ONLINE ? -INFINITY : 0.f, l1 = 0.f;
;     const int ktw_last = (q0w + 31) / 64;
;     ATT_WAITV(0); __builtin_amdgcn_s_barrier(); asm volatile("" ::: "memory");
; #pragma unroll
;     for (int i = 0; i < AL_PD; ++i) if (kt0 + i < nt) ATT_DMA(kt0 + i, i);
.LBB0_438:
	s_lshl_b64 s[8:9], s[12:13], 20
	s_lshl_b64 s[64:65], s[8:9], 1
	s_add_u32 s8, s78, s64
	s_addc_u32 s9, s79, s65
	v_and_b32_e32 v3, 63, v5
	s_add_u32 s40, s80, s64
	s_addc_u32 s41, s81, s65
	s_lshl_b32 s58, s22, 2
	v_lshrrev_b32_e32 v2, 4, v3
	v_or_b32_e32 v6, s58, v2
	v_ashrrev_i32_e32 v7, 31, v6
	v_lshlrev_b64 v[6:7], 8, v[6:7]
	s_ashr_i32 s23, s23, 4
	v_lshrrev_b32_e32 v8, 2, v5
	v_bitop3_b32 v0, s58, v5, v2 bitop3:0x36
	s_lshl_b32 s58, s22, 1
	v_bfi_b32 v8, -8, s23, v8
	v_lshl_add_u64 v[6:7], s[8:9], 0, v[6:7]
	s_lshl_b32 s8, s22, 10
	v_ashrrev_i32_e32 v9, 31, v8
	v_and_or_b32 v10, s58, 2, v4
	v_lshlrev_b32_e32 v0, 4, v0
	s_add_i32 s58, s8, 0x100
	s_lshl_b32 s8, s22, 8
	s_add_i32 s1, s38, 0x100
	v_lshlrev_b64 v[8:9], 8, v[8:9]
	v_lshlrev_b32_e32 v11, 3, v5
	v_and_b32_e32 v0, 0xf0, v0
	s_add_i32 s59, s8, 0x100
	s_lshr_b32 s1, s1, 6
	v_and_b32_e32 v190, 24, v11
	s_sub_i32 s33, s33, s39
	v_lshl_add_u64 v[184:185], v[6:7], 0, v[0:1]
	v_lshl_add_u64 v[6:7], s[40:41], 0, v[8:9]
	v_lshlrev_b32_e32 v0, 6, v10
	s_add_i32 s59, s59, 0x20000
	v_lshl_add_u64 v[6:7], v[6:7], 0, v[0:1]
	v_lshlrev_b32_e32 v0, 1, v190
	s_waitcnt vmcnt(0)
	v_cndmask_b32_e64 v212, 0, v208, s[100:101]
	v_mov_b32_e32 v213, v212
	v_mov_b32_e32 v214, v212
	v_mov_b32_e32 v215, v212
	v_mov_b32_e32 v216, v212
	v_mov_b32_e32 v217, v212
	v_mov_b32_e32 v218, v212
	v_mov_b32_e32 v219, v212
	v_mov_b32_e32 v220, v212
	v_mov_b32_e32 v221, v212
	v_mov_b32_e32 v222, v212
	v_mov_b32_e32 v223, v212
	v_mov_b32_e32 v224, v212
	v_mov_b32_e32 v225, v212
	v_mov_b32_e32 v226, v212
	v_mov_b32_e32 v227, v212
	v_readlane_b32 vcc_hi, v255, 8
	v_readfirstlane_b32 vcc_lo, v208
	s_nop 1
	v_mov_b32_e32 v252, vcc_hi
	v_add_f32_e32 v252, vcc_lo, v252
	v_add_f32_e32 v252, 0x42800000, v252
	v_mov_b32_e32 v251, 1
	s_barrier
	s_cmp_lt_i32 s33, s1
	v_lshl_add_u64 v[186:187], v[6:7], 0, v[0:1]
	v_lshlrev_b32_e32 v0, 2, v3
	s_cselect_b64 s[8:9], -1, 0
	v_lshlrev_b64 v[182:183], 7, v[180:181]
	v_lshlrev_b32_e32 v96, 3, v4
	v_lshl_add_u64 v[188:189], s[66:67], 0, v[0:1]
	s_and_b64 vcc, exec, s[8:9]
	s_cbranch_vccnz .LBB0_461
	s_add_i32 s22, s33, 1
	s_cmp_ge_i32 s22, s1
	s_cbranch_scc0 .LBB0_462

; #define LAS __attribute__((address_space(3)))
; #define MFMA32(a, b, c) __builtin_amdgcn_mfma_f32_32x32x16_bf16((a), (b), (c), 0, 0, 0)
; template <int MODE>
; __device__ __forceinline__ void attn_unit(const Params& P, LAS unsigned char* lds, const int b, const int h, const int qb) {
;     ...
;         if (kt <= ktw_last) {
;             const LAS unsigned char* Kb = lds + cur * 32768;
;             const int kbase = kt * 64 + 8 * hh;
;             u32x4 pk1[4];
;             f32x16 s[2];
; #pragma unroll
;             for (int i = 0; i < 16; ++i) { s[0][i] = 0.f; s[1][i] = 0.f; }
;             s16x4 va[8], vb[8], vc[8], vd[8];
;             const unsigned vaddr = (unsigned)(uintptr_t)(Kb + vra);
;             if constexpr (MODE == 1) {
;                 bf16x8 kf[8];
;                 const unsigned kb_ = (unsigned)(uintptr_t)Kb + kra, c0 = mp * 8 + hh;
;                 k_issue4(kf, kb_ + (((c0) ^ kswz) << 4), kb_ + (((c0 + 2) ^ kswz) << 4), kb_ + (((c0 + 4) ^ kswz) << 4), kb_ + (((c0 + 6) ^ kswz) << 4));
;                 v_issue<0>(va, vaddr);
;                 k_wait<8>(kf);
; #pragma unroll
;                 for (int ks = 0; ks < 4; ++ks) { s[0] = MFMA32(kf[2 * ks], Qf[ks], s[0]); s[1] = MFMA32(kf[2 * ks + 1], Qf[ks], s[1]); }
;                 v_issue<1>(vb, vaddr);
;             } else {
; #pragma unroll
;             for (int ks = 0; ks < NQ; ++ks) {
;                 const unsigned chunk = mp * 8 + 2 * ks + hh;
;                 const unsigned off = kra + ((chunk ^ kswz) << 4);
;                 const bf16x8 a0 = *(const LAS bf16x8*)(Kb + off), a1 = *(const LAS bf16x8*)(Kb + off + 8192);
;                 s[0] = MFMA32(a0, Qf[ks], s[0]); s[1] = MFMA32(a1, Qf[ks], s[1]);
;             }
;             v_issue<0>(va, vaddr);
;             }
;             if (FOX) {
;                 const LAS float* cl = (const LAS float*)(lds + AL_CLS + (cur * 8 + w) * 256) + 8 * hh;
; #pragma unroll
;                 for (int blk = 0; blk < 2; ++blk)
; #pragma unroll
;                     for (int j4 = 0; j4 < 4; ++j4) { const f32x4 c = *(const LAS f32x4*)(cl + 32 * blk + 16 * (j4 >> 1) + 4 * (j4 & 1));
; #pragma unroll
;                         for (int e = 0; e < 4; ++e) s[blk][4 * j4 + e] -= c[e]; }
.LBB0_455:
	s_cmp_gt_i32 s40, s22
	s_cbranch_scc1 .LBB0_444
	v_readfirstlane_b32 s8, v251
	s_cmp_eq_u32 s8, 0
	s_cbranch_scc1 .Lfox_nochk
	s_and_b32 s8, s67, 3
	s_lshl_b32 s8, s8, 11
	s_add_i32 s8, s8, s59
	s_addk_i32 s8, 0xfc
	v_mov_b32_e32 v0, s8
	ds_read_b32 v0, v0
	s_waitcnt lgkmcnt(0)
	v_sub_f32_e32 v0, v252, v0
	v_cmp_gt_f32_e32 vcc, 0, v0
	s_cbranch_vccnz .LBB0_444
	v_mov_b32_e32 v251, 0
.Lfox_nochk:
	s_and_b32 s8, s67, 3
	s_lshl_b32 s9, s8, 15
	s_addk_i32 s9, 0x100
	v_add_u32_e32 v0, s9, v192
	v_add3_u32 v0, v0, v195, v193
	v_add3_u32 v206, v0, v190, s73
	v_add_u32_e32 v0, s9, v194
	v_add_u32_e32 v6, v0, v197
	ds_read_b128 v[2:5], v6
	ds_read_b128 v[6:9], v6 offset:8192
	s_cmp_le_i32 s38, s0
	s_waitcnt lgkmcnt(0)
	v_mfma_f32_32x32x16_bf16 v[114:129], v[2:5], v[130:133], v[212:227]
	v_mfma_f32_32x32x16_bf16 v[98:113], v[6:9], v[130:133], v[212:227]
	v_add_u32_e32 v6, v0, v198
	ds_read_b128 v[2:5], v6
	ds_read_b128 v[6:9], v6 offset:8192
	s_waitcnt lgkmcnt(0)
	v_mfma_f32_32x32x16_bf16 v[114:129], v[2:5], v[134:137], v[114:129]
	v_mfma_f32_32x32x16_bf16 v[98:113], v[6:9], v[134:137], v[98:113]
	v_add_u32_e32 v6, v0, v199
	ds_read_b128 v[2:5], v6
	ds_read_b128 v[6:9], v6 offset:8192
	s_waitcnt lgkmcnt(0)
	v_mfma_f32_32x32x16_bf16 v[114:129], v[2:5], v[138:141], v[114:129]
	v_mfma_f32_32x32x16_bf16 v[98:113], v[6:9], v[138:141], v[98:113]
	v_add_u32_e32 v6, v0, v200
	ds_read_b128 v[2:5], v6
	ds_read_b128 v[6:9], v6 offset:8192
	s_waitcnt lgkmcnt(0)
	v_mfma_f32_32x32x16_bf16 v[114:129], v[2:5], v[142:145], v[114:129]
	v_mfma_f32_32x32x16_bf16 v[98:113], v[6:9], v[142:145], v[98:113]
	v_add_u32_e32 v6, v0, v201
	ds_read_b128 v[2:5], v6
	ds_read_b128 v[6:9], v6 offset:8192
	s_waitcnt lgkmcnt(0)
	v_mfma_f32_32x32x16_bf16 v[114:129], v[2:5], v[146:149], v[114:129]
	v_mfma_f32_32x32x16_bf16 v[98:113], v[6:9], v[146:149], v[98:113]
	v_add_u32_e32 v6, v0, v202
	ds_read_b128 v[2:5], v6
	ds_read_b128 v[6:9], v6 offset:8192
	s_waitcnt lgkmcnt(0)
	v_mfma_f32_32x32x16_bf16 v[114:129], v[2:5], v[150:153], v[114:129]
	v_mfma_f32_32x32x16_bf16 v[98:113], v[6:9], v[150:153], v[98:113]
	v_add_u32_e32 v6, v0, v203
	ds_read_b128 v[2:5], v6
	ds_read_b128 v[6:9], v6 offset:8192
	v_add_u32_e32 v0, v0, v204
	s_waitcnt lgkmcnt(0)
	v_mfma_f32_32x32x16_bf16 v[114:129], v[2:5], v[154:157], v[114:129]
	v_mfma_f32_32x32x16_bf16 v[98:113], v[6:9], v[154:157], v[98:113]
	ds_read_b128 v[2:5], v0
	ds_read_b128 v[6:9], v0 offset:8192
	v_lshl_add_u32 v0, s8, 11, v196
	ds_read_b64_tr_b16 v[174:175], v206 offset:0
	ds_read_b64_tr_b16 v[176:177], v206 offset:0x100
	ds_read_b64_tr_b16 v[170:171], v206 offset:0x200
	ds_read_b64_tr_b16 v[172:173], v206 offset:0x300
	ds_read_b64_tr_b16 v[166:167], v206 offset:0x400
	ds_read_b64_tr_b16 v[168:169], v206 offset:0x500
	ds_read_b64_tr_b16 v[162:163], v206 offset:0x600
	ds_read_b64_tr_b16 v[164:165], v206 offset:0x700
	s_waitcnt lgkmcnt(0)
	v_mfma_f32_32x32x16_bf16 v[114:129], v[2:5], v[158:161], v[114:129]
	v_mfma_f32_32x32x16_bf16 v[98:113], v[6:9], v[158:161], v[98:113]
	ds_read_b128 v[2:5], v0
	ds_read_b128 v[6:9], v0 offset:16
	ds_read_b128 v[10:13], v0 offset:64
	ds_read_b128 v[82:85], v0 offset:80
	s_waitcnt lgkmcnt(0)
	s_nop 5
	v_sub_f32_e32 v95, v117, v5
	v_sub_f32_e32 v91, v121, v9
	v_sub_f32_e32 v87, v123, v11
	v_sub_f32_e32 v81, v129, v85
	v_sub_f32_e32 v80, v128, v84
	v_sub_f32_e32 v85, v125, v13
	v_sub_f32_e32 v84, v124, v12
	v_sub_f32_e32 v86, v122, v10
	v_sub_f32_e32 v88, v120, v8
	v_sub_f32_e32 v93, v119, v7
	v_sub_f32_e32 v90, v118, v6
	v_sub_f32_e32 v92, v116, v4
	v_sub_f32_e32 v97, v115, v3
	v_sub_f32_e32 v94, v114, v2
	ds_read_b128 v[114:117], v0 offset:128
	ds_read_b128 v[2:5], v0 offset:144
	ds_read_b128 v[6:9], v0 offset:192
	ds_read_b128 v[10:13], v0 offset:208
	v_sub_f32_e32 v83, v127, v83
	v_sub_f32_e32 v82, v126, v82
	s_waitcnt lgkmcnt(0)
	v_sub_f32_e32 v89, v99, v115
	v_sub_f32_e32 v0, v98, v114
	v_sub_f32_e32 v15, v113, v13
	v_sub_f32_e32 v14, v112, v12
	v_sub_f32_e32 v13, v111, v11
	v_sub_f32_e32 v12, v110, v10
	v_sub_f32_e32 v11, v109, v9
	v_sub_f32_e32 v10, v108, v8
	v_sub_f32_e32 v9, v107, v7
	v_sub_f32_e32 v8, v106, v6
	v_sub_f32_e32 v7, v105, v5
	v_sub_f32_e32 v6, v104, v4
	v_sub_f32_e32 v5, v103, v3
	v_sub_f32_e32 v4, v102, v2
	v_sub_f32_e32 v3, v101, v117
	v_sub_f32_e32 v2, v100, v116
	s_cbranch_scc1 .LBB0_458
; template <int MODE>
; __device__ __forceinline__ void attn_unit(const Params& P, LAS unsigned char* lds, const int b, const int h, const int qb) {
;     ...
;             if (kt * 64 + 63 > q0w) {
; #pragma unroll
;                 for (int blk = 0; blk < 2; ++blk)
; #pragma unroll
;                     for (int i = 0; i < 16; ++i) { if (kbase + 32 * blk + 16 * (i >> 3) + (i & 7) > q) s[blk][i] = -INFINITY; }
;             }
	v_add_u32_e32 v98, s38, v96
	v_subrev_u32_e32 v99, 63, v98
	v_cmp_le_i32_e32 vcc, v99, v180
	v_cmp_lt_i32_e64 s[8:9], v99, v180
	v_subrev_u32_e32 v99, 61, v98
	v_cndmask_b32_e32 v94, v231, v94, vcc
	v_cmp_le_i32_e32 vcc, v99, v180
	v_subrev_u32_e32 v99, 60, v98
	v_cndmask_b32_e64 v97, v231, v97, s[8:9]
	v_cndmask_b32_e32 v92, v231, v92, vcc
	v_cmp_le_i32_e32 vcc, v99, v180
	v_subrev_u32_e32 v99, 59, v98
	s_nop 0
	v_cndmask_b32_e32 v95, v231, v95, vcc
	v_cmp_le_i32_e32 vcc, v99, v180
	v_subrev_u32_e32 v99, 58, v98
	s_nop 0
	v_cndmask_b32_e32 v90, v231, v90, vcc
	v_cmp_le_i32_e32 vcc, v99, v180
	v_subrev_u32_e32 v99, 57, v98
	s_nop 0
	v_cndmask_b32_e32 v93, v231, v93, vcc
	v_cmp_le_i32_e32 vcc, v99, v180
	v_subrev_u32_e32 v99, 56, v98
	s_nop 0
	v_cndmask_b32_e32 v88, v231, v88, vcc
	v_cmp_le_i32_e32 vcc, v99, v180
	v_subrev_u32_e32 v99, 47, v98
	s_nop 0
	v_cndmask_b32_e32 v91, v231, v91, vcc
	v_cmp_le_i32_e32 vcc, v99, v180
	v_subrev_u32_e32 v99, 46, v98
	s_nop 0
	v_cndmask_b32_e32 v86, v231, v86, vcc
	v_cmp_le_i32_e32 vcc, v99, v180
	v_subrev_u32_e32 v99, 45, v98
	s_nop 0
	v_cndmask_b32_e32 v87, v231, v87, vcc
	v_cmp_le_i32_e32 vcc, v99, v180
	v_subrev_u32_e32 v99, 44, v98
	s_nop 0
	v_cndmask_b32_e32 v84, v231, v84, vcc
	v_cmp_le_i32_e32 vcc, v99, v180
	v_subrev_u32_e32 v99, 43, v98
	s_nop 0
	v_cndmask_b32_e32 v85, v231, v85, vcc
	v_cmp_le_i32_e32 vcc, v99, v180
	v_subrev_u32_e32 v99, 42, v98
	s_nop 0
	v_cndmask_b32_e32 v82, v231, v82, vcc
	v_cmp_le_i32_e32 vcc, v99, v180
	v_subrev_u32_e32 v99, 41, v98
	s_nop 0
	v_cndmask_b32_e32 v83, v231, v83, vcc
	v_cmp_le_i32_e32 vcc, v99, v180
	v_subrev_u32_e32 v99, 40, v98
	s_nop 0
	v_cndmask_b32_e32 v80, v231, v80, vcc
	v_cmp_le_i32_e32 vcc, v99, v180
	v_subrev_u32_e32 v99, 31, v98
	s_nop 0
	v_cndmask_b32_e32 v81, v231, v81, vcc
	v_cmp_le_i32_e32 vcc, v99, v180
	v_subrev_u32_e32 v99, 30, v98
	s_nop 0
	v_cndmask_b32_e32 v0, v231, v0, vcc
	v_cmp_le_i32_e32 vcc, v99, v180
	v_subrev_u32_e32 v99, 29, v98
	s_nop 0
	v_cndmask_b32_e32 v89, v231, v89, vcc
	v_cmp_le_i32_e32 vcc, v99, v180
	v_subrev_u32_e32 v99, 28, v98
	s_nop 0
	v_cndmask_b32_e32 v2, v231, v2, vcc
	v_cmp_le_i32_e32 vcc, v99, v180
	v_subrev_u32_e32 v99, 27, v98
	s_nop 0
	v_cndmask_b32_e32 v3, v231, v3, vcc
	v_cmp_le_i32_e32 vcc, v99, v180
	v_subrev_u32_e32 v99, 26, v98
	s_nop 0
	v_cndmask_b32_e32 v4, v231, v4, vcc
	v_cmp_le_i32_e32 vcc, v99, v180
	v_subrev_u32_e32 v99, 25, v98
	s_nop 0
	v_cndmask_b32_e32 v5, v231, v5, vcc
	v_cmp_le_i32_e32 vcc, v99, v180
	v_subrev_u32_e32 v99, 24, v98
	s_nop 0
	v_cndmask_b32_e32 v6, v231, v6, vcc
	v_cmp_le_i32_e32 vcc, v99, v180
	v_add_u32_e32 v99, -15, v98
	s_nop 0
	v_cndmask_b32_e32 v7, v231, v7, vcc
	v_cmp_le_i32_e32 vcc, v99, v180
	v_add_u32_e32 v99, -14, v98
	s_nop 0
	v_cndmask_b32_e32 v8, v231, v8, vcc
	v_cmp_le_i32_e32 vcc, v99, v180
	v_add_u32_e32 v99, -13, v98
	s_nop 0
	v_cndmask_b32_e32 v9, v231, v9, vcc
	v_cmp_le_i32_e32 vcc, v99, v180
	v_add_u32_e32 v99, -12, v98
	s_nop 0
	v_cndmask_b32_e32 v10, v231, v10, vcc
	v_cmp_le_i32_e32 vcc, v99, v180
	v_add_u32_e32 v99, -11, v98
	s_nop 0
	v_cndmask_b32_e32 v11, v231, v11, vcc
	v_cmp_le_i32_e32 vcc, v99, v180
	v_add_u32_e32 v99, -10, v98
	s_nop 0
	v_cndmask_b32_e32 v12, v231, v12, vcc
	v_cmp_le_i32_e32 vcc, v99, v180
	v_add_u32_e32 v99, -9, v98
	v_add_u32_e32 v98, -8, v98
	v_cndmask_b32_e32 v13, v231, v13, vcc
	v_cmp_le_i32_e32 vcc, v99, v180
	s_nop 1
	v_cndmask_b32_e32 v14, v231, v14, vcc
	v_cmp_le_i32_e32 vcc, v98, v180
	s_nop 1
	v_cndmask_b32_e32 v15, v231, v15, vcc
